# best_b + P1 row loop: the four store-draining waits at the inner loop header removed (first entry waits once before the loop)
# baseline (speedup 1.0000x reference)
.LBB0_181:
	s_ashr_i32 s13, s12, 31
	s_lshr_b32 s0, s13, 21
	s_add_i32 s0, s12, s0
	s_ashr_i32 s0, s0, 11
	s_mul_hi_i32 s1, s0, 0x9000
	s_mul_i32 s0, s0, 0x9000
	s_add_u32 s0, s86, s0
	s_addc_u32 s1, s87, s1
	s_add_u32 s14, s0, 0x1000
	s_addc_u32 s15, s1, 0
	global_load_dwordx4 v[28:31], v78, s[14:15]
	global_load_dwordx4 v[32:35], v79, s[14:15]
	global_load_dwordx4 v[36:39], v[50:51], off
	global_load_dwordx4 v[40:43], v[50:51], off offset:1024
	global_load_dwordx4 v[56:59], v80, s[14:15]
	global_load_dwordx4 v[60:63], v81, s[14:15]
	global_load_dwordx4 v[0:3], v78, s[0:1]
	global_load_dwordx4 v[4:7], v78, s[0:1] offset:1024
	global_load_dwordx4 v[66:69], v[50:51], off offset:2048
	global_load_dwordx4 v[84:87], v[50:51], off offset:3072
	global_load_dwordx4 v[8:11], v78, s[0:1] offset:2048
	global_load_dwordx4 v[12:15], v78, s[0:1] offset:3072
	s_lshl_b64 s[0:1], s[12:13], 12
	v_lshl_add_u64 v[54:55], v[48:49], 0, s[0:1]
	global_load_dwordx4 v[44:47], v[54:55], off
	global_load_dwordx4 v[24:27], v[54:55], off offset:1024
	global_load_dwordx4 v[20:23], v[54:55], off offset:2048
	global_load_dwordx4 v[16:19], v[54:55], off offset:3072
	v_mov_b64_e32 v[54:55], v[52:53]
	s_add_i32 s13, s12, 0xf8
	s_mov_b32 s14, s12
	s_waitcnt vmcnt(15)
	v_pk_add_f32 v[30:31], v[30:31], 1.0 op_sel_hi:[1,0]
	v_pk_add_f32 v[28:29], v[28:29], 1.0 op_sel_hi:[1,0]
	s_waitcnt vmcnt(14)
	v_pk_add_f32 v[34:35], v[34:35], 1.0 op_sel_hi:[1,0]
	v_pk_add_f32 v[32:33], v[32:33], 1.0 op_sel_hi:[1,0]
	s_waitcnt vmcnt(11)
	v_pk_add_f32 v[64:65], v[58:59], 1.0 op_sel_hi:[1,0]
	v_pk_add_f32 v[70:71], v[56:57], 1.0 op_sel_hi:[1,0]
	s_waitcnt vmcnt(10)
	v_pk_add_f32 v[88:89], v[62:63], 1.0 op_sel_hi:[1,0]
	v_pk_add_f32 v[90:91], v[60:61], 1.0 op_sel_hi:[1,0]
	v_pk_mul_f32 v[56:57], v[38:39], v[30:31]
	v_pk_mul_f32 v[58:59], v[36:37], v[28:29]
	v_pk_mul_f32 v[60:61], v[42:43], v[34:35]
	v_pk_mul_f32 v[62:63], v[40:41], v[32:33]
	s_waitcnt vmcnt(7)
	v_pk_mul_f32 v[64:65], v[68:69], v[64:65]
	v_pk_mul_f32 v[66:67], v[66:67], v[70:71]
	s_waitcnt vmcnt(6)
	v_pk_mul_f32 v[68:69], v[86:87], v[88:89]
	v_pk_mul_f32 v[70:71], v[84:85], v[90:91]
	s_waitcnt vmcnt(0)
	s_branch .LBB0_183

.LBB0_183:
	s_mov_b32 s0, s14
	s_add_i32 s14, s14, 8
	s_cmp_ge_i32 s0, s13
	s_cselect_b64 s[16:17], -1, 0
	s_cmp_lt_i32 s0, s13
	v_mov_b32_e32 v28, v44
	v_mov_b32_e32 v29, v45
	v_mov_b32_e32 v30, v46
	v_mov_b32_e32 v31, v47
	v_mov_b32_e32 v32, v24
	v_mov_b32_e32 v33, v25
	v_mov_b32_e32 v34, v26
	v_mov_b32_e32 v35, v27
	v_mov_b32_e32 v36, v20
	v_mov_b32_e32 v37, v21
	v_mov_b32_e32 v38, v22
	v_mov_b32_e32 v39, v23
	v_mov_b32_e32 v40, v16
	v_mov_b32_e32 v41, v17
	v_mov_b32_e32 v42, v18
	v_mov_b32_e32 v43, v19
	s_cbranch_scc0 .LBB0_182
	s_ashr_i32 s15, s14, 31
	s_lshl_b64 s[0:1], s[14:15], 12
	v_lshl_add_u64 v[84:85], v[48:49], 0, s[0:1]
	global_load_dwordx4 v[28:31], v[84:85], off
	global_load_dwordx4 v[32:35], v[84:85], off offset:1024
	global_load_dwordx4 v[36:39], v[84:85], off offset:2048
	global_load_dwordx4 v[40:43], v[84:85], off offset:3072
	s_branch .LBB0_182
